# attention tile fast paths: interior window tiles use negm directly as QK C operand; MoBA past-block and NSA non-diagonal selected tiles skip the general mask-flag computation
# speedup vs baseline: 1.0090x; 1.0090x over previous
.LBB0_909:
	s_lshr_b32 s54, s13, 2
	s_cmp_ge_i32 s54, s93
	s_cselect_b64 s[50:51], -1, 0
	s_cbranch_scc0 .Lme_fast
	s_mov_b64 s[14:15], -1
	s_and_b64 vcc, exec, s[50:51]
	s_mov_b64 s[4:5], -1
	s_cbranch_vccz .LBB0_911
	s_and_b32 s4, s3, 0x80
	v_subrev_u32_e32 v48, s4, v154
	v_min_i32_e32 v213, 63, v48
	s_mov_b64 s[4:5], 0

.LBB0_924:
	s_cmp_eq_u64 s[50:51], 0
	s_cbranch_scc1 .Lmo_fast
	s_mov_b64 s[14:15], -1
	s_and_b64 vcc, exec, s[50:51]
	s_mov_b64 s[4:5], -1
	s_cbranch_vccz .LBB0_926
	s_and_b32 s4, s3, 0x80
	v_subrev_u32_e32 v48, s4, v192
	v_min_i32_e32 v149, 63, v48
	s_cbranch_execz .LBB0_927
	s_branch .LBB0_928

.Lme_fast:
	v_lshrrev_b32_e32 v48, s54, v146
	v_and_b32_e32 v48, 1, v48
	v_cmp_eq_u32_e32 vcc, 1, v48
	s_cbranch_vccz .LBB0_921
	v_add_u32_e32 v124, v159, v132
	s_nop 0
	v_cndmask_b32_e64 v48, v210, 0, vcc
	v_pk_add_f32 v[62:63], v[46:47], v[48:49] op_sel_hi:[1,0]
	v_pk_add_f32 v[60:61], v[44:45], v[48:49] op_sel_hi:[1,0]
	v_pk_add_f32 v[58:59], v[42:43], v[48:49] op_sel_hi:[1,0]
	v_pk_add_f32 v[56:57], v[40:41], v[48:49] op_sel_hi:[1,0]
	v_pk_add_f32 v[54:55], v[38:39], v[48:49] op_sel_hi:[1,0]
	v_pk_add_f32 v[52:53], v[36:37], v[48:49] op_sel_hi:[1,0]
	v_pk_add_f32 v[50:51], v[34:35], v[48:49] op_sel_hi:[1,0]
	v_pk_add_f32 v[48:49], v[32:33], v[48:49] op_sel_hi:[1,0]
	ds_read_b128 v[112:115], v124
	ds_read_b128 v[116:119], v124 offset:32
	s_waitcnt lgkmcnt(1)
	v_mfma_f32_32x32x16_bf16 v[64:79], v[112:115], v[80:83], v[48:63]
	ds_read_b128 v[112:115], v124 offset:4608
	ds_read_b128 v[120:123], v124 offset:4640
	s_waitcnt lgkmcnt(1)
	v_mfma_f32_32x32x16_bf16 v[48:63], v[112:115], v[80:83], v[48:63]
	v_mfma_f32_32x32x16_bf16 v[64:79], v[116:119], v[84:87], v[64:79]
	ds_read_b128 v[112:115], v124 offset:64
	ds_read_b128 v[116:119], v124 offset:96
	s_waitcnt lgkmcnt(2)
	v_mfma_f32_32x32x16_bf16 v[48:63], v[120:123], v[84:87], v[48:63]
	s_waitcnt lgkmcnt(1)
	v_mfma_f32_32x32x16_bf16 v[64:79], v[112:115], v[88:91], v[64:79]
	ds_read_b128 v[112:115], v124 offset:4672
	ds_read_b128 v[214:217], v124 offset:4704
	s_waitcnt lgkmcnt(1)
	v_mfma_f32_32x32x16_bf16 v[48:63], v[112:115], v[88:91], v[48:63]
	v_mfma_f32_32x32x16_bf16 v[64:79], v[116:119], v[92:95], v[64:79]
	ds_read_b64_tr_b16 v[120:121], v160 offset:18432
	ds_read_b64_tr_b16 v[122:123], v160 offset:19968
	ds_read_b64_tr_b16 v[114:115], v160 offset:20032
	ds_read_b64_tr_b16 v[112:113], v160 offset:18496
	ds_read_b64_tr_b16 v[124:125], v160 offset:21504
	ds_read_b64_tr_b16 v[126:127], v160 offset:23040
	ds_read_b64_tr_b16 v[118:119], v160 offset:23104
	ds_read_b64_tr_b16 v[116:117], v160 offset:21568
	s_waitcnt lgkmcnt(8)
	v_mfma_f32_32x32x16_bf16 v[48:63], v[214:217], v[92:95], v[48:63]
	s_branch .LBB0_918
.Lmo_fast:
	v_lshrrev_b32_e32 v48, s54, v146
	v_and_b32_e32 v48, 1, v48
	v_cmp_eq_u32_e32 vcc, 1, v48
	s_cbranch_vccz .LBB0_936
	v_add_u32_e32 v124, v159, v132
	s_nop 0
	v_cndmask_b32_e64 v48, v210, 0, vcc
	v_pk_add_f32 v[62:63], v[46:47], v[48:49] op_sel_hi:[1,0]
	v_pk_add_f32 v[60:61], v[44:45], v[48:49] op_sel_hi:[1,0]
	v_pk_add_f32 v[58:59], v[42:43], v[48:49] op_sel_hi:[1,0]
	v_pk_add_f32 v[56:57], v[40:41], v[48:49] op_sel_hi:[1,0]
	v_pk_add_f32 v[54:55], v[38:39], v[48:49] op_sel_hi:[1,0]
	v_pk_add_f32 v[52:53], v[36:37], v[48:49] op_sel_hi:[1,0]
	v_pk_add_f32 v[50:51], v[34:35], v[48:49] op_sel_hi:[1,0]
	v_pk_add_f32 v[48:49], v[32:33], v[48:49] op_sel_hi:[1,0]
	ds_read_b128 v[112:115], v124 offset:9216
	ds_read_b128 v[116:119], v124 offset:9248
	s_waitcnt lgkmcnt(1)
	v_mfma_f32_32x32x16_bf16 v[64:79], v[112:115], v[80:83], v[48:63]
	ds_read_b128 v[112:115], v124 offset:13824
	ds_read_b128 v[120:123], v124 offset:13856
	s_waitcnt lgkmcnt(1)
	v_mfma_f32_32x32x16_bf16 v[48:63], v[112:115], v[80:83], v[48:63]
	v_mfma_f32_32x32x16_bf16 v[64:79], v[116:119], v[84:87], v[64:79]
	ds_read_b128 v[112:115], v124 offset:9280
	ds_read_b128 v[116:119], v124 offset:9312
	s_waitcnt lgkmcnt(2)
	v_mfma_f32_32x32x16_bf16 v[48:63], v[120:123], v[84:87], v[48:63]
	s_waitcnt lgkmcnt(1)
	v_mfma_f32_32x32x16_bf16 v[64:79], v[112:115], v[88:91], v[64:79]
	ds_read_b128 v[112:115], v124 offset:13888
	ds_read_b128 v[212:215], v124 offset:13920
	s_waitcnt lgkmcnt(1)
	v_mfma_f32_32x32x16_bf16 v[48:63], v[112:115], v[88:91], v[48:63]
	v_mfma_f32_32x32x16_bf16 v[64:79], v[116:119], v[92:95], v[64:79]
	ds_read_b64_tr_b16 v[120:121], v160 offset:30720
	ds_read_b64_tr_b16 v[122:123], v160 offset:32256
	ds_read_b64_tr_b16 v[114:115], v160 offset:32320
	ds_read_b64_tr_b16 v[112:113], v160 offset:30784
	ds_read_b64_tr_b16 v[124:125], v160 offset:33792
	ds_read_b64_tr_b16 v[126:127], v160 offset:35328
	ds_read_b64_tr_b16 v[118:119], v160 offset:35392
	ds_read_b64_tr_b16 v[116:117], v160 offset:33856
	s_waitcnt lgkmcnt(8)
	v_mfma_f32_32x32x16_bf16 v[48:63], v[212:215], v[92:95], v[48:63]
	s_branch .LBB0_933

.LBB0_1015:
	s_add_i32 s13, s2, -3
	s_waitcnt lgkmcnt(2)
	v_lshrrev_b32_e32 v48, s13, v128
	v_and_b32_e32 v48, 1, v48
	v_cmp_eq_u32_e64 s[14:15], 1, v48
	v_bfe_u32 v48, v128, s13, 1
	s_add_i32 s12, s1, s2
	v_cmp_ne_u32_e32 vcc, 0, v48
	s_cbranch_vccz .LBB0_1023
	s_cmp_eq_u32 s12, 3
	s_cbranch_scc1 .Lse_slow
	v_cndmask_b32_e64 v48, v210, 0, s[14:15]
	v_pk_add_f32 v[62:63], v[46:47], v[48:49] op_sel_hi:[1,0]
	v_pk_add_f32 v[60:61], v[44:45], v[48:49] op_sel_hi:[1,0]
	v_pk_add_f32 v[58:59], v[42:43], v[48:49] op_sel_hi:[1,0]
	v_pk_add_f32 v[56:57], v[40:41], v[48:49] op_sel_hi:[1,0]
	v_pk_add_f32 v[54:55], v[38:39], v[48:49] op_sel_hi:[1,0]
	v_pk_add_f32 v[52:53], v[36:37], v[48:49] op_sel_hi:[1,0]
	v_pk_add_f32 v[50:51], v[34:35], v[48:49] op_sel_hi:[1,0]
	v_pk_add_f32 v[48:49], v[32:33], v[48:49] op_sel_hi:[1,0]
	ds_read_b128 v[112:115], v131
	ds_read_b128 v[116:119], v131 offset:32
	s_waitcnt lgkmcnt(1)
	v_mfma_f32_32x32x16_bf16 v[64:79], v[112:115], v[80:83], v[48:63]
	ds_read_b128 v[112:115], v131 offset:4608
	ds_read_b128 v[120:123], v131 offset:4640
	s_waitcnt lgkmcnt(1)
	v_mfma_f32_32x32x16_bf16 v[48:63], v[112:115], v[80:83], v[48:63]
	v_mfma_f32_32x32x16_bf16 v[64:79], v[116:119], v[84:87], v[64:79]
	ds_read_b128 v[112:115], v131 offset:64
	ds_read_b128 v[116:119], v131 offset:96
	s_waitcnt lgkmcnt(2)
	v_mfma_f32_32x32x16_bf16 v[48:63], v[120:123], v[84:87], v[48:63]
	s_waitcnt lgkmcnt(1)
	v_mfma_f32_32x32x16_bf16 v[64:79], v[112:115], v[88:91], v[64:79]
	ds_read_b128 v[112:115], v131 offset:4672
	ds_read_b128 v[218:221], v131 offset:4704
	s_waitcnt lgkmcnt(1)
	v_mfma_f32_32x32x16_bf16 v[48:63], v[112:115], v[88:91], v[48:63]
	v_mfma_f32_32x32x16_bf16 v[64:79], v[116:119], v[92:95], v[64:79]
	ds_read_b64_tr_b16 v[120:121], v160 offset:18432
	ds_read_b64_tr_b16 v[122:123], v160 offset:19968
	ds_read_b64_tr_b16 v[114:115], v160 offset:20032
	ds_read_b64_tr_b16 v[112:113], v160 offset:18496
	ds_read_b64_tr_b16 v[124:125], v160 offset:21504
	ds_read_b64_tr_b16 v[126:127], v160 offset:23040
	ds_read_b64_tr_b16 v[118:119], v160 offset:23104
	ds_read_b64_tr_b16 v[116:117], v160 offset:21568
	s_waitcnt lgkmcnt(8)
	v_mfma_f32_32x32x16_bf16 v[48:63], v[218:221], v[92:95], v[48:63]
	s_branch .LBB0_1020
.Lse_slow:
	s_cmp_eq_u32 s12, 3
	s_cselect_b64 vcc, -1, 0
	v_cndmask_b32_e32 v216, 63, v193, vcc
	v_cmp_eq_u32_e32 vcc, 63, v216
	s_xor_b64 s[4:5], s[14:15], -1
	ds_read_b128 v[112:115], v131
	ds_read_b128 v[116:119], v131 offset:32
	s_or_b64 s[18:19], vcc, s[4:5]
	v_cndmask_b32_e64 v48, 0, 1, s[18:19]
	s_and_b64 s[16:17], vcc, s[14:15]
	v_cmp_ne_u32_e32 vcc, 0, v48
	s_cmp_lg_u64 vcc, exec
	s_cselect_b64 s[18:19], -1, 0
	s_or_b64 s[16:17], s[16:17], s[18:19]
	v_cndmask_b32_e64 v48, v210, 0, s[16:17]
	v_pk_add_f32 v[62:63], v[46:47], v[48:49] op_sel_hi:[1,0]
	v_pk_add_f32 v[60:61], v[44:45], v[48:49] op_sel_hi:[1,0]
	v_pk_add_f32 v[58:59], v[42:43], v[48:49] op_sel_hi:[1,0]
	v_pk_add_f32 v[56:57], v[40:41], v[48:49] op_sel_hi:[1,0]
	v_pk_add_f32 v[54:55], v[38:39], v[48:49] op_sel_hi:[1,0]
	v_pk_add_f32 v[52:53], v[36:37], v[48:49] op_sel_hi:[1,0]
	v_pk_add_f32 v[50:51], v[34:35], v[48:49] op_sel_hi:[1,0]
	v_pk_add_f32 v[48:49], v[32:33], v[48:49] op_sel_hi:[1,0]
	s_cmp_eq_u64 vcc, exec
	s_waitcnt lgkmcnt(1)
	v_mfma_f32_32x32x16_bf16 v[64:79], v[112:115], v[80:83], v[48:63]
	ds_read_b128 v[112:115], v131 offset:4608
	ds_read_b128 v[120:123], v131 offset:4640
	s_waitcnt lgkmcnt(1)
	v_mfma_f32_32x32x16_bf16 v[48:63], v[112:115], v[80:83], v[48:63]
	v_mfma_f32_32x32x16_bf16 v[64:79], v[116:119], v[84:87], v[64:79]
	ds_read_b128 v[112:115], v131 offset:64
	ds_read_b128 v[116:119], v131 offset:96
	s_waitcnt lgkmcnt(2)
	v_mfma_f32_32x32x16_bf16 v[48:63], v[120:123], v[84:87], v[48:63]
	s_waitcnt lgkmcnt(1)
	v_mfma_f32_32x32x16_bf16 v[64:79], v[112:115], v[88:91], v[64:79]
	ds_read_b128 v[112:115], v131 offset:4672
	ds_read_b128 v[218:221], v131 offset:4704
	s_waitcnt lgkmcnt(1)
	v_mfma_f32_32x32x16_bf16 v[48:63], v[112:115], v[88:91], v[48:63]
	v_mfma_f32_32x32x16_bf16 v[64:79], v[116:119], v[92:95], v[64:79]
	ds_read_b64_tr_b16 v[120:121], v160 offset:18432
	ds_read_b64_tr_b16 v[122:123], v160 offset:19968
	ds_read_b64_tr_b16 v[114:115], v160 offset:20032
	ds_read_b64_tr_b16 v[112:113], v160 offset:18496
	ds_read_b64_tr_b16 v[124:125], v160 offset:21504
	ds_read_b64_tr_b16 v[126:127], v160 offset:23040
	ds_read_b64_tr_b16 v[118:119], v160 offset:23104
	ds_read_b64_tr_b16 v[116:117], v160 offset:21568
	s_waitcnt lgkmcnt(8)
	v_mfma_f32_32x32x16_bf16 v[48:63], v[218:221], v[92:95], v[48:63]
	s_cbranch_scc1 .LBB0_1020
	v_cmp_le_u32_e64 s[16:17], v161, v216
	v_cmp_le_u32_e64 s[18:19], v162, v216
	v_cmp_le_u32_e64 s[20:21], v164, v216
	v_cmp_le_u32_e64 s[22:23], v166, v216
	v_cmp_le_u32_e64 s[24:25], v168, v216
	v_cmp_le_u32_e64 s[26:27], v170, v216
	v_cmp_le_u32_e64 s[28:29], v172, v216
	v_cmp_le_u32_e64 s[30:31], v174, v216
	v_cmp_le_u32_e64 s[34:35], v176, v216
	v_cmp_le_u32_e64 s[36:37], v178, v216
	v_cmp_le_u32_e64 s[38:39], v180, v216
	v_cmp_le_u32_e64 s[40:41], v182, v216
	v_cmp_le_u32_e64 s[42:43], v184, v216
	v_cmp_le_u32_e64 s[44:45], v186, v216
	v_cmp_le_u32_e64 s[46:47], v189, v216
	s_and_b64 s[16:17], s[14:15], s[16:17]
	s_and_b64 s[18:19], s[14:15], s[18:19]
	s_and_b64 s[20:21], s[14:15], s[20:21]
	s_and_b64 s[22:23], s[14:15], s[22:23]
	s_and_b64 s[24:25], s[14:15], s[24:25]
	s_and_b64 s[26:27], s[14:15], s[26:27]
	s_and_b64 s[28:29], s[14:15], s[28:29]
	s_and_b64 s[30:31], s[14:15], s[30:31]
	s_and_b64 s[34:35], s[14:15], s[34:35]
	s_and_b64 s[36:37], s[14:15], s[36:37]
	s_and_b64 s[38:39], s[14:15], s[38:39]
	s_and_b64 s[40:41], s[14:15], s[40:41]
	s_and_b64 s[42:43], s[14:15], s[42:43]
	s_and_b64 s[44:45], s[14:15], s[44:45]
	s_and_b64 s[46:47], s[14:15], s[46:47]
	v_cmp_gt_u32_e64 s[48:49], v191, v216
	v_cmp_le_u32_e32 vcc, v138, v216
	v_cndmask_b32_e64 v48, v210, v48, s[16:17]
	v_cmp_lt_u32_e64 s[16:17], v138, v216
	v_cndmask_b32_e64 v49, v210, v49, s[18:19]
	v_cmp_le_u32_e64 s[18:19], v163, v216
	v_cndmask_b32_e64 v50, v210, v50, s[20:21]
	v_cmp_le_u32_e64 s[20:21], v165, v216
	v_cndmask_b32_e64 v51, v210, v51, s[22:23]
	v_cmp_le_u32_e64 s[22:23], v167, v216
	v_cndmask_b32_e64 v52, v210, v52, s[24:25]
	v_cmp_le_u32_e64 s[24:25], v169, v216
	v_cndmask_b32_e64 v53, v210, v53, s[26:27]
	v_cmp_le_u32_e64 s[26:27], v171, v216
	v_cndmask_b32_e64 v54, v210, v54, s[28:29]
	v_cmp_le_u32_e64 s[28:29], v173, v216
	v_cndmask_b32_e64 v55, v210, v55, s[30:31]
	v_cmp_le_u32_e64 s[30:31], v175, v216
	v_cndmask_b32_e64 v56, v210, v56, s[34:35]
	v_cmp_le_u32_e64 s[34:35], v177, v216
	v_cndmask_b32_e64 v57, v210, v57, s[36:37]
	v_cmp_le_u32_e64 s[36:37], v179, v216
	v_cndmask_b32_e64 v58, v210, v58, s[38:39]
	v_cmp_le_u32_e64 s[38:39], v181, v216
	v_cndmask_b32_e64 v59, v210, v59, s[40:41]
	v_cmp_le_u32_e64 s[40:41], v183, v216
	v_cndmask_b32_e64 v60, v210, v60, s[42:43]
	v_cmp_le_u32_e64 s[42:43], v185, v216
	v_cndmask_b32_e64 v61, v210, v61, s[44:45]
	v_cmp_le_u32_e64 s[44:45], v187, v216
	v_cndmask_b32_e64 v62, v210, v62, s[46:47]
	v_cmp_le_u32_e64 s[46:47], v190, v216
	s_or_b64 s[48:49], s[4:5], s[48:49]
	s_and_saveexec_b64 s[4:5], s[48:49]
	v_mov_b32_e32 v63, s33
	s_or_b64 exec, exec, s[4:5]
	s_and_b64 vcc, s[14:15], vcc
	v_cndmask_b32_e32 v64, v210, v64, vcc
	s_and_b64 vcc, s[14:15], s[16:17]
	v_cndmask_b32_e32 v65, v210, v65, vcc
	s_and_b64 vcc, s[14:15], s[18:19]
	v_cndmask_b32_e32 v66, v210, v66, vcc
	s_and_b64 vcc, s[14:15], s[20:21]
	v_cndmask_b32_e32 v67, v210, v67, vcc
	s_and_b64 vcc, s[14:15], s[22:23]
	v_cndmask_b32_e32 v68, v210, v68, vcc
	s_and_b64 vcc, s[14:15], s[24:25]
	v_cndmask_b32_e32 v69, v210, v69, vcc
	s_and_b64 vcc, s[14:15], s[26:27]
	v_cndmask_b32_e32 v70, v210, v70, vcc
	s_and_b64 vcc, s[14:15], s[28:29]
	v_cndmask_b32_e32 v71, v210, v71, vcc
	s_and_b64 vcc, s[14:15], s[30:31]
	v_cndmask_b32_e32 v72, v210, v72, vcc
	s_and_b64 vcc, s[14:15], s[34:35]
	v_cndmask_b32_e32 v73, v210, v73, vcc
	s_and_b64 vcc, s[14:15], s[36:37]
	v_cndmask_b32_e32 v74, v210, v74, vcc
	s_and_b64 vcc, s[14:15], s[38:39]
	v_cndmask_b32_e32 v75, v210, v75, vcc
	s_and_b64 vcc, s[14:15], s[40:41]
	v_cndmask_b32_e32 v76, v210, v76, vcc
	s_and_b64 vcc, s[14:15], s[42:43]
	v_cndmask_b32_e32 v77, v210, v77, vcc
	s_and_b64 vcc, s[14:15], s[44:45]
	v_cndmask_b32_e32 v78, v210, v78, vcc
	s_and_b64 vcc, s[14:15], s[46:47]
	v_cndmask_b32_e32 v79, v210, v79, vcc

.LBB0_1026:
	s_add_i32 s4, s2, -2
	v_lshrrev_b32_e32 v48, s4, v128
	v_and_b32_e32 v48, 1, v48
	v_cmp_eq_u32_e64 s[14:15], 1, v48
	v_bfe_u32 v48, v128, s4, 1
	v_cmp_ne_u32_e32 vcc, 0, v48
	s_cbranch_vccz .LBB0_1012
	s_cmp_eq_u32 s12, 2
	s_cbranch_scc1 .Lso_slow
	v_cndmask_b32_e64 v48, v210, 0, s[14:15]
	v_pk_add_f32 v[62:63], v[46:47], v[48:49] op_sel_hi:[1,0]
	v_pk_add_f32 v[60:61], v[44:45], v[48:49] op_sel_hi:[1,0]
	v_pk_add_f32 v[58:59], v[42:43], v[48:49] op_sel_hi:[1,0]
	v_pk_add_f32 v[56:57], v[40:41], v[48:49] op_sel_hi:[1,0]
	v_pk_add_f32 v[54:55], v[38:39], v[48:49] op_sel_hi:[1,0]
	v_pk_add_f32 v[52:53], v[36:37], v[48:49] op_sel_hi:[1,0]
	v_pk_add_f32 v[50:51], v[34:35], v[48:49] op_sel_hi:[1,0]
	v_pk_add_f32 v[48:49], v[32:33], v[48:49] op_sel_hi:[1,0]
	ds_read_b128 v[112:115], v131 offset:9216
	ds_read_b128 v[116:119], v131 offset:9248
	s_waitcnt lgkmcnt(1)
	v_mfma_f32_32x32x16_bf16 v[64:79], v[112:115], v[80:83], v[48:63]
	ds_read_b128 v[112:115], v131 offset:13824
	ds_read_b128 v[120:123], v131 offset:13856
	s_waitcnt lgkmcnt(1)
	v_mfma_f32_32x32x16_bf16 v[48:63], v[112:115], v[80:83], v[48:63]
	v_mfma_f32_32x32x16_bf16 v[64:79], v[116:119], v[84:87], v[64:79]
	ds_read_b128 v[112:115], v131 offset:9280
	ds_read_b128 v[116:119], v131 offset:9312
	s_waitcnt lgkmcnt(2)
	v_mfma_f32_32x32x16_bf16 v[48:63], v[120:123], v[84:87], v[48:63]
	s_waitcnt lgkmcnt(1)
	v_mfma_f32_32x32x16_bf16 v[64:79], v[112:115], v[88:91], v[64:79]
	ds_read_b128 v[112:115], v131 offset:13888
	ds_read_b128 v[218:221], v131 offset:13920
	s_waitcnt lgkmcnt(1)
	v_mfma_f32_32x32x16_bf16 v[48:63], v[112:115], v[88:91], v[48:63]
	v_mfma_f32_32x32x16_bf16 v[64:79], v[116:119], v[92:95], v[64:79]
	ds_read_b64_tr_b16 v[120:121], v160 offset:30720
	ds_read_b64_tr_b16 v[122:123], v160 offset:32256
	ds_read_b64_tr_b16 v[114:115], v160 offset:32320
	ds_read_b64_tr_b16 v[112:113], v160 offset:30784
	ds_read_b64_tr_b16 v[124:125], v160 offset:33792
	ds_read_b64_tr_b16 v[126:127], v160 offset:35328
	ds_read_b64_tr_b16 v[118:119], v160 offset:35392
	ds_read_b64_tr_b16 v[116:117], v160 offset:33856
	s_waitcnt lgkmcnt(8)
	v_mfma_f32_32x32x16_bf16 v[48:63], v[218:221], v[92:95], v[48:63]
	s_branch .LBB0_1031
.Lso_slow:
	s_cmp_eq_u32 s12, 2
	s_cselect_b64 vcc, -1, 0
	v_cndmask_b32_e32 v216, 63, v193, vcc
	v_cmp_eq_u32_e32 vcc, 63, v216
	s_xor_b64 s[4:5], s[14:15], -1
	ds_read_b128 v[112:115], v131 offset:9216
	ds_read_b128 v[116:119], v131 offset:9248
	s_or_b64 s[16:17], vcc, s[4:5]
	v_cndmask_b32_e64 v48, 0, 1, s[16:17]
	s_and_b64 s[12:13], vcc, s[14:15]
	v_cmp_ne_u32_e32 vcc, 0, v48
	s_cmp_lg_u64 vcc, exec
	s_cselect_b64 s[16:17], -1, 0
	s_or_b64 s[12:13], s[12:13], s[16:17]
	v_cndmask_b32_e64 v48, v210, 0, s[12:13]
	v_pk_add_f32 v[62:63], v[46:47], v[48:49] op_sel_hi:[1,0]
	v_pk_add_f32 v[60:61], v[44:45], v[48:49] op_sel_hi:[1,0]
	v_pk_add_f32 v[58:59], v[42:43], v[48:49] op_sel_hi:[1,0]
	v_pk_add_f32 v[56:57], v[40:41], v[48:49] op_sel_hi:[1,0]
	v_pk_add_f32 v[54:55], v[38:39], v[48:49] op_sel_hi:[1,0]
	v_pk_add_f32 v[52:53], v[36:37], v[48:49] op_sel_hi:[1,0]
	v_pk_add_f32 v[50:51], v[34:35], v[48:49] op_sel_hi:[1,0]
	v_pk_add_f32 v[48:49], v[32:33], v[48:49] op_sel_hi:[1,0]
	s_cmp_eq_u64 vcc, exec
	s_waitcnt lgkmcnt(1)
	v_mfma_f32_32x32x16_bf16 v[64:79], v[112:115], v[80:83], v[48:63]
	ds_read_b128 v[112:115], v131 offset:13824
	ds_read_b128 v[120:123], v131 offset:13856
	s_waitcnt lgkmcnt(1)
	v_mfma_f32_32x32x16_bf16 v[48:63], v[112:115], v[80:83], v[48:63]
	v_mfma_f32_32x32x16_bf16 v[64:79], v[116:119], v[84:87], v[64:79]
	ds_read_b128 v[112:115], v131 offset:9280
	ds_read_b128 v[116:119], v131 offset:9312
	s_waitcnt lgkmcnt(2)
	v_mfma_f32_32x32x16_bf16 v[48:63], v[120:123], v[84:87], v[48:63]
	s_waitcnt lgkmcnt(1)
	v_mfma_f32_32x32x16_bf16 v[64:79], v[112:115], v[88:91], v[64:79]
	ds_read_b128 v[112:115], v131 offset:13888
	ds_read_b128 v[218:221], v131 offset:13920
	s_waitcnt lgkmcnt(1)
	v_mfma_f32_32x32x16_bf16 v[48:63], v[112:115], v[88:91], v[48:63]
	v_mfma_f32_32x32x16_bf16 v[64:79], v[116:119], v[92:95], v[64:79]
	ds_read_b64_tr_b16 v[120:121], v160 offset:30720
	ds_read_b64_tr_b16 v[122:123], v160 offset:32256
	ds_read_b64_tr_b16 v[114:115], v160 offset:32320
	ds_read_b64_tr_b16 v[112:113], v160 offset:30784
	ds_read_b64_tr_b16 v[124:125], v160 offset:33792
	ds_read_b64_tr_b16 v[126:127], v160 offset:35328
	ds_read_b64_tr_b16 v[118:119], v160 offset:35392
	ds_read_b64_tr_b16 v[116:117], v160 offset:33856
	s_waitcnt lgkmcnt(8)
	v_mfma_f32_32x32x16_bf16 v[48:63], v[218:221], v[92:95], v[48:63]
	s_cbranch_scc1 .LBB0_1031
	v_cmp_le_u32_e64 s[16:17], v161, v216
	v_cmp_le_u32_e64 s[18:19], v162, v216
	v_cmp_le_u32_e64 s[20:21], v164, v216
	v_cmp_le_u32_e64 s[22:23], v166, v216
	v_cmp_le_u32_e64 s[24:25], v168, v216
	v_cmp_le_u32_e64 s[26:27], v170, v216
	v_cmp_le_u32_e64 s[28:29], v172, v216
	v_cmp_le_u32_e64 s[30:31], v174, v216
	v_cmp_le_u32_e64 s[34:35], v176, v216
	v_cmp_le_u32_e64 s[36:37], v178, v216
	v_cmp_le_u32_e64 s[38:39], v180, v216
	v_cmp_le_u32_e64 s[40:41], v182, v216
	v_cmp_le_u32_e64 s[42:43], v184, v216
	v_cmp_le_u32_e64 s[44:45], v186, v216
	v_cmp_le_u32_e64 s[46:47], v189, v216
	s_and_b64 s[16:17], s[14:15], s[16:17]
	s_and_b64 s[18:19], s[14:15], s[18:19]
	s_and_b64 s[20:21], s[14:15], s[20:21]
	s_and_b64 s[22:23], s[14:15], s[22:23]
	s_and_b64 s[24:25], s[14:15], s[24:25]
	s_and_b64 s[26:27], s[14:15], s[26:27]
	s_and_b64 s[28:29], s[14:15], s[28:29]
	s_and_b64 s[30:31], s[14:15], s[30:31]
	s_and_b64 s[34:35], s[14:15], s[34:35]
	s_and_b64 s[36:37], s[14:15], s[36:37]
	s_and_b64 s[38:39], s[14:15], s[38:39]
	s_and_b64 s[40:41], s[14:15], s[40:41]
	s_and_b64 s[42:43], s[14:15], s[42:43]
	s_and_b64 s[44:45], s[14:15], s[44:45]
	s_and_b64 s[46:47], s[14:15], s[46:47]
	v_cmp_gt_u32_e64 s[48:49], v191, v216
	v_cmp_le_u32_e32 vcc, v138, v216
	v_cndmask_b32_e64 v48, v210, v48, s[16:17]
	v_cmp_lt_u32_e64 s[16:17], v138, v216
	v_cndmask_b32_e64 v49, v210, v49, s[18:19]
	v_cmp_le_u32_e64 s[18:19], v163, v216
	v_cndmask_b32_e64 v50, v210, v50, s[20:21]
	v_cmp_le_u32_e64 s[20:21], v165, v216
	v_cndmask_b32_e64 v51, v210, v51, s[22:23]
	v_cmp_le_u32_e64 s[22:23], v167, v216
	v_cndmask_b32_e64 v52, v210, v52, s[24:25]
	v_cmp_le_u32_e64 s[24:25], v169, v216
	v_cndmask_b32_e64 v53, v210, v53, s[26:27]
	v_cmp_le_u32_e64 s[26:27], v171, v216
	v_cndmask_b32_e64 v54, v210, v54, s[28:29]
	v_cmp_le_u32_e64 s[28:29], v173, v216
	v_cndmask_b32_e64 v55, v210, v55, s[30:31]
	v_cmp_le_u32_e64 s[30:31], v175, v216
	v_cndmask_b32_e64 v56, v210, v56, s[34:35]
	v_cmp_le_u32_e64 s[34:35], v177, v216
	v_cndmask_b32_e64 v57, v210, v57, s[36:37]
	v_cmp_le_u32_e64 s[36:37], v179, v216
	v_cndmask_b32_e64 v58, v210, v58, s[38:39]
	v_cmp_le_u32_e64 s[38:39], v181, v216
	v_cndmask_b32_e64 v59, v210, v59, s[40:41]
	v_cmp_le_u32_e64 s[40:41], v183, v216
	v_cndmask_b32_e64 v60, v210, v60, s[42:43]
	v_cmp_le_u32_e64 s[42:43], v185, v216
	v_cndmask_b32_e64 v61, v210, v61, s[44:45]
	v_cmp_le_u32_e64 s[44:45], v187, v216
	v_cndmask_b32_e64 v62, v210, v62, s[46:47]
	v_cmp_le_u32_e64 s[46:47], v190, v216
	s_or_b64 s[12:13], s[4:5], s[48:49]
	s_and_saveexec_b64 s[4:5], s[12:13]
	v_mov_b32_e32 v63, s33
	s_or_b64 exec, exec, s[4:5]
	s_and_b64 vcc, s[14:15], vcc
	v_cndmask_b32_e32 v64, v210, v64, vcc
	s_and_b64 vcc, s[14:15], s[16:17]
	v_cndmask_b32_e32 v65, v210, v65, vcc
	s_and_b64 vcc, s[14:15], s[18:19]
	v_cndmask_b32_e32 v66, v210, v66, vcc
	s_and_b64 vcc, s[14:15], s[20:21]
	v_cndmask_b32_e32 v67, v210, v67, vcc
	s_and_b64 vcc, s[14:15], s[22:23]
	v_cndmask_b32_e32 v68, v210, v68, vcc
	s_and_b64 vcc, s[14:15], s[24:25]
	v_cndmask_b32_e32 v69, v210, v69, vcc
	s_and_b64 vcc, s[14:15], s[26:27]
	v_cndmask_b32_e32 v70, v210, v70, vcc
	s_and_b64 vcc, s[14:15], s[28:29]
	v_cndmask_b32_e32 v71, v210, v71, vcc
	s_and_b64 vcc, s[14:15], s[30:31]
	v_cndmask_b32_e32 v72, v210, v72, vcc
	s_and_b64 vcc, s[14:15], s[34:35]
	v_cndmask_b32_e32 v73, v210, v73, vcc
	s_and_b64 vcc, s[14:15], s[36:37]
	v_cndmask_b32_e32 v74, v210, v74, vcc
	s_and_b64 vcc, s[14:15], s[38:39]
	v_cndmask_b32_e32 v75, v210, v75, vcc
	s_and_b64 vcc, s[14:15], s[40:41]
	v_cndmask_b32_e32 v76, v210, v76, vcc
	s_and_b64 vcc, s[14:15], s[42:43]
	v_cndmask_b32_e32 v77, v210, v77, vcc
	s_and_b64 vcc, s[14:15], s[44:45]
	v_cndmask_b32_e32 v78, v210, v78, vcc
	s_and_b64 vcc, s[14:15], s[46:47]
	v_cndmask_b32_e32 v79, v210, v79, vcc

.LBB0_1039:
	s_cmp_eq_u32 s3, s13
	s_cbranch_scc1 .Lwe_slow
	s_cmp_eq_u32 s1, s13
	s_cbranch_scc1 .Lwe_slow
	ds_read_b128 v[112:115], v131
	ds_read_b128 v[116:119], v131 offset:32
	s_waitcnt lgkmcnt(1)
	v_mfma_f32_32x32x16_bf16 v[64:79], v[112:115], v[80:83], v[32:47]
	ds_read_b128 v[112:115], v131 offset:4608
	ds_read_b128 v[120:123], v131 offset:4640
	s_waitcnt lgkmcnt(1)
	v_mfma_f32_32x32x16_bf16 v[48:63], v[112:115], v[80:83], v[32:47]
	v_mfma_f32_32x32x16_bf16 v[64:79], v[116:119], v[84:87], v[64:79]
	ds_read_b128 v[112:115], v131 offset:64
	ds_read_b128 v[116:119], v131 offset:96
	s_waitcnt lgkmcnt(2)
	v_mfma_f32_32x32x16_bf16 v[48:63], v[120:123], v[84:87], v[48:63]
	s_waitcnt lgkmcnt(1)
	v_mfma_f32_32x32x16_bf16 v[64:79], v[112:115], v[88:91], v[64:79]
	ds_read_b128 v[112:115], v131 offset:4672
	ds_read_b128 v[218:221], v131 offset:4704
	s_waitcnt lgkmcnt(1)
	v_mfma_f32_32x32x16_bf16 v[48:63], v[112:115], v[88:91], v[48:63]
	v_mfma_f32_32x32x16_bf16 v[64:79], v[116:119], v[92:95], v[64:79]
	ds_read_b64_tr_b16 v[120:121], v160 offset:18432
	ds_read_b64_tr_b16 v[122:123], v160 offset:19968
	ds_read_b64_tr_b16 v[114:115], v160 offset:20032
	ds_read_b64_tr_b16 v[112:113], v160 offset:18496
	ds_read_b64_tr_b16 v[124:125], v160 offset:21504
	ds_read_b64_tr_b16 v[126:127], v160 offset:23040
	ds_read_b64_tr_b16 v[118:119], v160 offset:23104
	ds_read_b64_tr_b16 v[116:117], v160 offset:21568
	s_waitcnt lgkmcnt(8)
	v_mfma_f32_32x32x16_bf16 v[48:63], v[218:221], v[92:95], v[48:63]
	s_branch .LBB0_1106

.LBB0_1112:
	s_cmp_eq_u32 s2, s13
	s_cbranch_scc1 .Lwo_slow
	s_cmp_eq_u32 s91, s13
	s_cbranch_scc1 .Lwo_slow
	ds_read_b128 v[112:115], v131 offset:9216
	ds_read_b128 v[116:119], v131 offset:9248
	s_waitcnt lgkmcnt(1)
	v_mfma_f32_32x32x16_bf16 v[64:79], v[112:115], v[80:83], v[32:47]
	ds_read_b128 v[112:115], v131 offset:13824
	ds_read_b128 v[120:123], v131 offset:13856
	s_waitcnt lgkmcnt(1)
	v_mfma_f32_32x32x16_bf16 v[48:63], v[112:115], v[80:83], v[32:47]
	v_mfma_f32_32x32x16_bf16 v[64:79], v[116:119], v[84:87], v[64:79]
	ds_read_b128 v[112:115], v131 offset:9280
	ds_read_b128 v[116:119], v131 offset:9312
	s_waitcnt lgkmcnt(2)
	v_mfma_f32_32x32x16_bf16 v[48:63], v[120:123], v[84:87], v[48:63]
	s_waitcnt lgkmcnt(1)
	v_mfma_f32_32x32x16_bf16 v[64:79], v[112:115], v[88:91], v[64:79]
	ds_read_b128 v[112:115], v131 offset:13888
	ds_read_b128 v[218:221], v131 offset:13920
	s_waitcnt lgkmcnt(1)
	v_mfma_f32_32x32x16_bf16 v[48:63], v[112:115], v[88:91], v[48:63]
	v_mfma_f32_32x32x16_bf16 v[64:79], v[116:119], v[92:95], v[64:79]
	ds_read_b64_tr_b16 v[120:121], v160 offset:30720
	ds_read_b64_tr_b16 v[122:123], v160 offset:32256
	ds_read_b64_tr_b16 v[114:115], v160 offset:32320
	ds_read_b64_tr_b16 v[112:113], v160 offset:30784
	ds_read_b64_tr_b16 v[124:125], v160 offset:33792
	ds_read_b64_tr_b16 v[126:127], v160 offset:35328
	ds_read_b64_tr_b16 v[118:119], v160 offset:35392
	ds_read_b64_tr_b16 v[116:117], v160 offset:33856
	s_waitcnt lgkmcnt(8)
	v_mfma_f32_32x32x16_bf16 v[48:63], v[218:221], v[92:95], v[48:63]
	s_branch .LBB0_1179
